# final y / P9 output stores write-through sc1 instead of nt (less dirty L2 at seam 8 and kernel end)
# baseline (speedup 1.0000x reference)
.LBB0_1667:
	s_or_b64 exec, exec, s[26:27]
	v_readlane_b32 s0, v253, 6
	v_readlane_b32 s12, v253, 18
	v_readlane_b32 s13, v253, 19
	s_waitcnt lgkmcnt(0)
	s_waitcnt lgkmcnt(0)
	s_barrier
	v_lshl_add_u64 v[128:129], v[156:157], 2, s[12:13]
	global_load_dwordx4 v[132:135], v[128:129], off
	global_load_dwordx4 v[136:139], v[128:129], off offset:64
	global_load_dwordx4 v[140:143], v[128:129], off offset:512
	global_load_dwordx4 v[160:163], v[128:129], off offset:576
	ds_read_b32 v164, v223 offset:0
	ds_read_b32 v166, v223 offset:64
	ds_read_b32 v168, v223 offset:128
	ds_read_b32 v170, v223 offset:192
	ds_read_b32 v172, v223 offset:512
	ds_read_b32 v174, v223 offset:576
	ds_read_b32 v176, v223 offset:640
	ds_read_b32 v178, v223 offset:704
	v_lshlrev_b32_e32 v180, 2, v148
	s_waitcnt vmcnt(0) lgkmcnt(0)
	v_mov_b32_e32 v181, v180
	v_pk_mul_f32 v[124:125], v[124:125], v[164:165] op_sel_hi:[1,0]
	v_pk_mul_f32 v[126:127], v[126:127], v[164:165] op_sel_hi:[1,0]
	v_pk_mul_f32 v[124:125], v[132:133], v[124:125]
	v_pk_mul_f32 v[126:127], v[134:135], v[126:127]
	global_store_dwordx4 v181, v[124:127], s[8:9] offset:0 sc1
	v_pk_mul_f32 v[120:121], v[120:121], v[164:165] op_sel_hi:[1,0]
	v_pk_mul_f32 v[122:123], v[122:123], v[164:165] op_sel_hi:[1,0]
	v_pk_mul_f32 v[120:121], v[136:137], v[120:121]
	v_pk_mul_f32 v[122:123], v[138:139], v[122:123]
	global_store_dwordx4 v181, v[120:123], s[8:9] offset:64 sc1
	v_pk_mul_f32 v[116:117], v[116:117], v[164:165] op_sel_hi:[1,0]
	v_pk_mul_f32 v[118:119], v[118:119], v[164:165] op_sel_hi:[1,0]
	v_pk_mul_f32 v[116:117], v[140:141], v[116:117]
	v_pk_mul_f32 v[118:119], v[142:143], v[118:119]
	global_store_dwordx4 v181, v[116:119], s[8:9] offset:512 sc1
	v_pk_mul_f32 v[108:109], v[108:109], v[164:165] op_sel_hi:[1,0]
	v_pk_mul_f32 v[110:111], v[110:111], v[164:165] op_sel_hi:[1,0]
	v_pk_mul_f32 v[108:109], v[160:161], v[108:109]
	v_pk_mul_f32 v[110:111], v[162:163], v[110:111]
	global_store_dwordx4 v181, v[108:111], s[8:9] offset:576 sc1
	v_add_u32_e32 v182, 0x20000, v180
	v_pk_mul_f32 v[112:113], v[112:113], v[166:167] op_sel_hi:[1,0]
	v_pk_mul_f32 v[114:115], v[114:115], v[166:167] op_sel_hi:[1,0]
	v_pk_mul_f32 v[112:113], v[132:133], v[112:113]
	v_pk_mul_f32 v[114:115], v[134:135], v[114:115]
	global_store_dwordx4 v182, v[112:115], s[8:9] offset:0 sc1
	v_pk_mul_f32 v[104:105], v[104:105], v[166:167] op_sel_hi:[1,0]
	v_pk_mul_f32 v[106:107], v[106:107], v[166:167] op_sel_hi:[1,0]
	v_pk_mul_f32 v[104:105], v[136:137], v[104:105]
	v_pk_mul_f32 v[106:107], v[138:139], v[106:107]
	global_store_dwordx4 v182, v[104:107], s[8:9] offset:64 sc1
	v_pk_mul_f32 v[100:101], v[100:101], v[166:167] op_sel_hi:[1,0]
	v_pk_mul_f32 v[102:103], v[102:103], v[166:167] op_sel_hi:[1,0]
	v_pk_mul_f32 v[100:101], v[140:141], v[100:101]
	v_pk_mul_f32 v[102:103], v[142:143], v[102:103]
	global_store_dwordx4 v182, v[100:103], s[8:9] offset:512 sc1
	v_pk_mul_f32 v[92:93], v[92:93], v[166:167] op_sel_hi:[1,0]
	v_pk_mul_f32 v[94:95], v[94:95], v[166:167] op_sel_hi:[1,0]
	v_pk_mul_f32 v[92:93], v[160:161], v[92:93]
	v_pk_mul_f32 v[94:95], v[162:163], v[94:95]
	global_store_dwordx4 v182, v[92:95], s[8:9] offset:576 sc1
	v_add_u32_e32 v181, 0x40000, v180
	v_pk_mul_f32 v[96:97], v[96:97], v[168:169] op_sel_hi:[1,0]
	v_pk_mul_f32 v[98:99], v[98:99], v[168:169] op_sel_hi:[1,0]
	v_pk_mul_f32 v[96:97], v[132:133], v[96:97]
	v_pk_mul_f32 v[98:99], v[134:135], v[98:99]
	global_store_dwordx4 v181, v[96:99], s[8:9] offset:0 sc1
	v_pk_mul_f32 v[88:89], v[88:89], v[168:169] op_sel_hi:[1,0]
	v_pk_mul_f32 v[90:91], v[90:91], v[168:169] op_sel_hi:[1,0]
	v_pk_mul_f32 v[88:89], v[136:137], v[88:89]
	v_pk_mul_f32 v[90:91], v[138:139], v[90:91]
	global_store_dwordx4 v181, v[88:91], s[8:9] offset:64 sc1
	v_pk_mul_f32 v[84:85], v[84:85], v[168:169] op_sel_hi:[1,0]
	v_pk_mul_f32 v[86:87], v[86:87], v[168:169] op_sel_hi:[1,0]
	v_pk_mul_f32 v[84:85], v[140:141], v[84:85]
	v_pk_mul_f32 v[86:87], v[142:143], v[86:87]
	global_store_dwordx4 v181, v[84:87], s[8:9] offset:512 sc1
	v_pk_mul_f32 v[76:77], v[76:77], v[168:169] op_sel_hi:[1,0]
	v_pk_mul_f32 v[78:79], v[78:79], v[168:169] op_sel_hi:[1,0]
	v_pk_mul_f32 v[76:77], v[160:161], v[76:77]
	v_pk_mul_f32 v[78:79], v[162:163], v[78:79]
	global_store_dwordx4 v181, v[76:79], s[8:9] offset:576 sc1
	v_add_u32_e32 v182, 0x60000, v180
	v_pk_mul_f32 v[80:81], v[80:81], v[170:171] op_sel_hi:[1,0]
	v_pk_mul_f32 v[82:83], v[82:83], v[170:171] op_sel_hi:[1,0]
	v_pk_mul_f32 v[80:81], v[132:133], v[80:81]
	v_pk_mul_f32 v[82:83], v[134:135], v[82:83]
	global_store_dwordx4 v182, v[80:83], s[8:9] offset:0 sc1
	v_pk_mul_f32 v[72:73], v[72:73], v[170:171] op_sel_hi:[1,0]
	v_pk_mul_f32 v[74:75], v[74:75], v[170:171] op_sel_hi:[1,0]
	v_pk_mul_f32 v[72:73], v[136:137], v[72:73]
	v_pk_mul_f32 v[74:75], v[138:139], v[74:75]
	global_store_dwordx4 v182, v[72:75], s[8:9] offset:64 sc1
	v_pk_mul_f32 v[68:69], v[68:69], v[170:171] op_sel_hi:[1,0]
	v_pk_mul_f32 v[70:71], v[70:71], v[170:171] op_sel_hi:[1,0]
	v_pk_mul_f32 v[68:69], v[140:141], v[68:69]
	v_pk_mul_f32 v[70:71], v[142:143], v[70:71]
	global_store_dwordx4 v182, v[68:71], s[8:9] offset:512 sc1
	v_pk_mul_f32 v[64:65], v[64:65], v[170:171] op_sel_hi:[1,0]
	v_pk_mul_f32 v[66:67], v[66:67], v[170:171] op_sel_hi:[1,0]
	v_pk_mul_f32 v[64:65], v[160:161], v[64:65]
	v_pk_mul_f32 v[66:67], v[162:163], v[66:67]
	global_store_dwordx4 v182, v[64:67], s[8:9] offset:576 sc1
	v_add_u32_e32 v181, 0x100000, v180
	v_pk_mul_f32 v[60:61], v[60:61], v[172:173] op_sel_hi:[1,0]
	v_pk_mul_f32 v[62:63], v[62:63], v[172:173] op_sel_hi:[1,0]
	v_pk_mul_f32 v[60:61], v[132:133], v[60:61]
	v_pk_mul_f32 v[62:63], v[134:135], v[62:63]
	global_store_dwordx4 v181, v[60:63], s[8:9] offset:0 sc1
	v_pk_mul_f32 v[56:57], v[56:57], v[172:173] op_sel_hi:[1,0]
	v_pk_mul_f32 v[58:59], v[58:59], v[172:173] op_sel_hi:[1,0]
	v_pk_mul_f32 v[56:57], v[136:137], v[56:57]
	v_pk_mul_f32 v[58:59], v[138:139], v[58:59]
	global_store_dwordx4 v181, v[56:59], s[8:9] offset:64 sc1
	v_pk_mul_f32 v[52:53], v[52:53], v[172:173] op_sel_hi:[1,0]
	v_pk_mul_f32 v[54:55], v[54:55], v[172:173] op_sel_hi:[1,0]
	v_pk_mul_f32 v[52:53], v[140:141], v[52:53]
	v_pk_mul_f32 v[54:55], v[142:143], v[54:55]
	global_store_dwordx4 v181, v[52:55], s[8:9] offset:512 sc1
	v_pk_mul_f32 v[44:45], v[44:45], v[172:173] op_sel_hi:[1,0]
	v_pk_mul_f32 v[46:47], v[46:47], v[172:173] op_sel_hi:[1,0]
	v_pk_mul_f32 v[44:45], v[160:161], v[44:45]
	v_pk_mul_f32 v[46:47], v[162:163], v[46:47]
	global_store_dwordx4 v181, v[44:47], s[8:9] offset:576 sc1
	v_add_u32_e32 v182, 0x120000, v180
	v_pk_mul_f32 v[48:49], v[48:49], v[174:175] op_sel_hi:[1,0]
	v_pk_mul_f32 v[50:51], v[50:51], v[174:175] op_sel_hi:[1,0]
	v_pk_mul_f32 v[48:49], v[132:133], v[48:49]
	v_pk_mul_f32 v[50:51], v[134:135], v[50:51]
	global_store_dwordx4 v182, v[48:51], s[8:9] offset:0 sc1
	v_pk_mul_f32 v[40:41], v[40:41], v[174:175] op_sel_hi:[1,0]
	v_pk_mul_f32 v[42:43], v[42:43], v[174:175] op_sel_hi:[1,0]
	v_pk_mul_f32 v[40:41], v[136:137], v[40:41]
	v_pk_mul_f32 v[42:43], v[138:139], v[42:43]
	global_store_dwordx4 v182, v[40:43], s[8:9] offset:64 sc1
	v_pk_mul_f32 v[36:37], v[36:37], v[174:175] op_sel_hi:[1,0]
	v_pk_mul_f32 v[38:39], v[38:39], v[174:175] op_sel_hi:[1,0]
	v_pk_mul_f32 v[36:37], v[140:141], v[36:37]
	v_pk_mul_f32 v[38:39], v[142:143], v[38:39]
	global_store_dwordx4 v182, v[36:39], s[8:9] offset:512 sc1
	v_pk_mul_f32 v[28:29], v[28:29], v[174:175] op_sel_hi:[1,0]
	v_pk_mul_f32 v[30:31], v[30:31], v[174:175] op_sel_hi:[1,0]
	v_pk_mul_f32 v[28:29], v[160:161], v[28:29]
	v_pk_mul_f32 v[30:31], v[162:163], v[30:31]
	global_store_dwordx4 v182, v[28:31], s[8:9] offset:576 sc1
	v_add_u32_e32 v181, 0x140000, v180
	v_pk_mul_f32 v[32:33], v[32:33], v[176:177] op_sel_hi:[1,0]
	v_pk_mul_f32 v[34:35], v[34:35], v[176:177] op_sel_hi:[1,0]
	v_pk_mul_f32 v[32:33], v[132:133], v[32:33]
	v_pk_mul_f32 v[34:35], v[134:135], v[34:35]
	global_store_dwordx4 v181, v[32:35], s[8:9] offset:0 sc1
	v_pk_mul_f32 v[24:25], v[24:25], v[176:177] op_sel_hi:[1,0]
	v_pk_mul_f32 v[26:27], v[26:27], v[176:177] op_sel_hi:[1,0]
	v_pk_mul_f32 v[24:25], v[136:137], v[24:25]
	v_pk_mul_f32 v[26:27], v[138:139], v[26:27]
	global_store_dwordx4 v181, v[24:27], s[8:9] offset:64 sc1
	v_pk_mul_f32 v[20:21], v[20:21], v[176:177] op_sel_hi:[1,0]
	v_pk_mul_f32 v[22:23], v[22:23], v[176:177] op_sel_hi:[1,0]
	v_pk_mul_f32 v[20:21], v[140:141], v[20:21]
	v_pk_mul_f32 v[22:23], v[142:143], v[22:23]
	global_store_dwordx4 v181, v[20:23], s[8:9] offset:512 sc1
	v_pk_mul_f32 v[12:13], v[12:13], v[176:177] op_sel_hi:[1,0]
	v_pk_mul_f32 v[14:15], v[14:15], v[176:177] op_sel_hi:[1,0]
	v_pk_mul_f32 v[12:13], v[160:161], v[12:13]
	v_pk_mul_f32 v[14:15], v[162:163], v[14:15]
	global_store_dwordx4 v181, v[12:15], s[8:9] offset:576 sc1
	v_add_u32_e32 v182, 0x160000, v180
	v_pk_mul_f32 v[16:17], v[16:17], v[178:179] op_sel_hi:[1,0]
	v_pk_mul_f32 v[18:19], v[18:19], v[178:179] op_sel_hi:[1,0]
	v_pk_mul_f32 v[16:17], v[132:133], v[16:17]
	v_pk_mul_f32 v[18:19], v[134:135], v[18:19]
	global_store_dwordx4 v182, v[16:19], s[8:9] offset:0 sc1
	v_pk_mul_f32 v[8:9], v[8:9], v[178:179] op_sel_hi:[1,0]
	v_pk_mul_f32 v[10:11], v[10:11], v[178:179] op_sel_hi:[1,0]
	v_pk_mul_f32 v[8:9], v[136:137], v[8:9]
	v_pk_mul_f32 v[10:11], v[138:139], v[10:11]
	global_store_dwordx4 v182, v[8:11], s[8:9] offset:64 sc1
	v_pk_mul_f32 v[4:5], v[4:5], v[178:179] op_sel_hi:[1,0]
	v_pk_mul_f32 v[6:7], v[6:7], v[178:179] op_sel_hi:[1,0]
	v_pk_mul_f32 v[4:5], v[140:141], v[4:5]
	v_pk_mul_f32 v[6:7], v[142:143], v[6:7]
	global_store_dwordx4 v182, v[4:7], s[8:9] offset:512 sc1
	v_pk_mul_f32 v[0:1], v[0:1], v[178:179] op_sel_hi:[1,0]
	v_pk_mul_f32 v[2:3], v[2:3], v[178:179] op_sel_hi:[1,0]
	v_pk_mul_f32 v[0:1], v[160:161], v[0:1]
	v_pk_mul_f32 v[2:3], v[162:163], v[2:3]
	global_store_dwordx4 v182, v[0:3], s[8:9] offset:576 sc1
	s_branch .LBB0_1668

.LBB0_1726:
	global_load_dwordx4 v[34:37], v[60:61], off
	s_waitcnt vmcnt(0)
	v_fmamk_f32 v32, v32, 0x3a000000, v56
	v_mul_f32_e32 v33, 0x4b800000, v32
	v_cmp_gt_f32_e32 vcc, s18, v32
	s_add_i32 s0, s0, s4
	s_add_u32 s6, s6, s8
	v_cndmask_b32_e32 v32, v32, v33, vcc
	v_rsq_f32_e32 v32, v32
	s_addc_u32 s7, s7, s9
	s_cmpk_lt_i32 s0, 0x2800
	v_mul_f32_e32 v33, 0x45800000, v32
	v_cndmask_b32_e32 v32, v32, v33, vcc
	v_pk_mul_f32 v[28:29], v[32:33], v[28:29] op_sel_hi:[0,1]
	v_pk_mul_f32 v[30:31], v[32:33], v[30:31] op_sel_hi:[0,1]
	v_pk_mul_f32 v[26:27], v[32:33], v[26:27] op_sel_hi:[0,1]
	v_pk_mul_f32 v[24:25], v[32:33], v[24:25] op_sel_hi:[0,1]
	v_pk_mul_f32 v[22:23], v[32:33], v[22:23] op_sel_hi:[0,1]
	v_pk_mul_f32 v[20:21], v[32:33], v[20:21] op_sel_hi:[0,1]
	v_pk_mul_f32 v[18:19], v[32:33], v[18:19] op_sel_hi:[0,1]
	v_pk_mul_f32 v[16:17], v[32:33], v[16:17] op_sel_hi:[0,1]
	v_pk_mul_f32 v[14:15], v[32:33], v[14:15] op_sel_hi:[0,1]
	v_pk_mul_f32 v[12:13], v[32:33], v[12:13] op_sel_hi:[0,1]
	v_pk_mul_f32 v[10:11], v[32:33], v[10:11] op_sel_hi:[0,1]
	v_pk_mul_f32 v[8:9], v[32:33], v[8:9] op_sel_hi:[0,1]
	v_pk_mul_f32 v[6:7], v[32:33], v[6:7] op_sel_hi:[0,1]
	v_pk_mul_f32 v[4:5], v[32:33], v[4:5] op_sel_hi:[0,1]
	v_pk_mul_f32 v[2:3], v[32:33], v[2:3] op_sel_hi:[0,1]
	v_pk_mul_f32 v[0:1], v[32:33], v[0:1] op_sel_hi:[0,1]
	v_pk_mul_f32 v[30:31], v[30:31], v[36:37]
	v_pk_mul_f32 v[28:29], v[28:29], v[34:35]
	global_store_dwordx4 v[70:71], v[28:31], off offset:-4096 sc1
	global_load_dwordx4 v[28:31], v[60:61], off offset:1024
	s_waitcnt vmcnt(0)
	v_pk_mul_f32 v[24:25], v[24:25], v[28:29]
	v_pk_mul_f32 v[26:27], v[26:27], v[30:31]
	global_store_dwordx4 v[70:71], v[24:27], off offset:-3072 sc1
	global_load_dwordx4 v[24:27], v[60:61], off offset:2048
	s_waitcnt vmcnt(0)
	v_pk_mul_f32 v[20:21], v[20:21], v[24:25]
	v_pk_mul_f32 v[22:23], v[22:23], v[26:27]
	global_store_dwordx4 v[70:71], v[20:23], off offset:-2048 sc1
	global_load_dwordx4 v[20:23], v[60:61], off offset:3072
	s_waitcnt vmcnt(0)
	v_pk_mul_f32 v[16:17], v[16:17], v[20:21]
	v_pk_mul_f32 v[18:19], v[18:19], v[22:23]
	global_store_dwordx4 v[70:71], v[16:19], off offset:-1024 sc1
	global_load_dwordx4 v[16:19], v[62:63], off
	s_waitcnt vmcnt(0)
	v_pk_mul_f32 v[12:13], v[12:13], v[16:17]
	v_pk_mul_f32 v[14:15], v[14:15], v[18:19]
	global_store_dwordx4 v[70:71], v[12:15], off sc1
	global_load_dwordx4 v[12:15], v[64:65], off
	s_waitcnt vmcnt(0)
	v_pk_mul_f32 v[8:9], v[8:9], v[12:13]
	v_pk_mul_f32 v[10:11], v[10:11], v[14:15]
	global_store_dwordx4 v[70:71], v[8:11], off offset:1024 sc1
	global_load_dwordx4 v[8:11], v[66:67], off
	s_waitcnt vmcnt(0)
	v_pk_mul_f32 v[4:5], v[4:5], v[8:9]
	v_pk_mul_f32 v[6:7], v[6:7], v[10:11]
	global_store_dwordx4 v[70:71], v[4:7], off offset:2048 sc1
	global_load_dwordx4 v[4:7], v[68:69], off
	s_waitcnt vmcnt(0)
	v_pk_mul_f32 v[0:1], v[0:1], v[4:5]
	v_pk_mul_f32 v[2:3], v[2:3], v[6:7]
	global_store_dwordx4 v[70:71], v[0:3], off offset:3072 sc1
	v_lshl_add_u64 v[70:71], v[70:71], 0, s[10:11]
	s_cbranch_scc0 .LBB0_1731
